# Win epilogue diff q/k path: rope (cos,sin) computed with v_cos/v_sin instead of per-group table loads + full waits
# speedup vs baseline: 1.0249x; 1.0039x over previous
.LBB0_247:
	s_lshl_b32 s0, s16, 8
	v_readlane_b32 s1, v253, 37
	s_or_b32 s0, s0, s1
	v_lshlrev_b32_e32 v152, 3, v160
	v_add_u32_e32 v150, s0, v152
	s_cmp_gt_i32 s16, 7
	s_mov_b64 s[18:19], -1
	s_cbranch_scc1 .LBB0_269
	s_add_i32 s0, s16, -4
	s_cmp_lt_u32 s0, 2
	s_cselect_b64 s[18:19], -1, 0
	s_cmp_gt_u32 s0, 1
	s_cbranch_scc0 .LBB0_269
	s_cmp_gt_i32 s16, 3
	s_mov_b64 s[0:1], -1
	s_cbranch_scc0 .LBB0_267
	s_cmp_eq_u32 s16, 6
	s_cselect_b64 vcc, -1, 0
	v_readlane_b32 s44, v251, 49
	s_and_b64 s[0:1], vcc, exec
	v_readlane_b32 s50, v251, 55
	v_readlane_b32 s52, v251, 57
	v_readlane_b32 s51, v251, 56
	v_readlane_b32 s53, v251, 58
	s_cselect_b32 s1, s50, s52
	v_lshlrev_b32_e32 v136, 2, v160
	s_cselect_b32 s0, s51, s53
	s_add_u32 s22, s1, s6
	v_or_b32_e32 v130, 1, v136
	s_addc_u32 s23, s0, s7
	v_add_u32_e32 v131, 9, v136
	v_cmp_gt_i32_e64 s[0:1], 8, v130
	v_or_b32_e32 v132, 2, v136
	v_add_u32_e32 v128, 8, v136
	v_cmp_gt_i32_e64 s[42:43], 2, v160
	v_cndmask_b32_e64 v130, v131, v130, s[0:1]
	v_add_u32_e32 v133, 10, v136
	v_cmp_gt_i32_e64 s[0:1], 8, v132
	v_or_b32_e32 v134, 3, v136
	v_cndmask_b32_e64 v128, v128, v136, s[42:43]
	v_cndmask_b32_e64 v132, v133, v132, s[0:1]
	v_add_u32_e32 v135, 11, v136
	v_cmp_gt_i32_e64 s[0:1], 8, v134
	v_ashrrev_i32_e32 v129, 31, v128
	v_lshl_add_u64 v[128:129], v[128:129], 2, s[22:23]
	v_cndmask_b32_e64 v134, v135, v134, s[0:1]
	v_ashrrev_i32_e32 v131, 31, v130
	v_ashrrev_i32_e32 v133, 31, v132
	v_ashrrev_i32_e32 v135, 31, v134
	v_lshl_add_u64 v[130:131], v[130:131], 2, s[22:23]
	v_lshl_add_u64 v[132:133], v[132:133], 2, s[22:23]
	v_lshl_add_u64 v[134:135], v[134:135], 2, s[22:23]
	global_load_dword v174, v[128:129], off
	global_load_dword v159, v[130:131], off
	global_load_dword v156, v[132:133], off
	global_load_dword v155, v[134:135], off
	global_load_dword v157, v[134:135], off offset:32
	global_load_dword v154, v[132:133], off offset:32
	global_load_dword v175, v[130:131], off offset:32
	global_load_dword v158, v[128:129], off offset:32
	s_cmp_lt_i32 s20, 64
	v_and_b32_e32 v129, 4, v136
	s_cselect_b64 s[22:23], -1, 0
	s_cmp_gt_i32 s20, 63
	v_and_b32_e32 v189, 63, v185
	v_mov_b32_e32 v178, 0
	v_mov_b32_e32 v128, 1.0
	v_lshlrev_b32_e32 v153, 3, v129
	v_mov_b32_e32 v134, 1.0
	v_mov_b32_e32 v180, 0
	v_mov_b32_e32 v181, 1.0
	v_mov_b32_e32 v135, 0
	v_mov_b32_e32 v130, 1.0
	v_mov_b32_e32 v136, 0
	v_mov_b32_e32 v137, 1.0
	v_mov_b32_e32 v131, 0
	v_readlane_b32 s45, v251, 50
	v_readlane_b32 s46, v251, 51
	v_readlane_b32 s47, v251, 52
	v_readlane_b32 s48, v251, 53
	v_readlane_b32 s49, v251, 54
	v_readlane_b32 s54, v251, 59
	v_readlane_b32 s55, v251, 60
	v_readlane_b32 s56, v251, 61
	v_readlane_b32 s57, v251, 62
	v_readlane_b32 s58, v251, 63
	v_readlane_b32 s59, v252, 0
	s_cbranch_scc1 .LBB0_252
	v_bfe_u32 v129, v184, 6, 7
	v_cndmask_b32_e64 v129, v189, v129, s[42:43]
	v_cmp_ne_u32_e64 s[98:99], 0, v153
	v_cvt_f32_u32_e32 v132, v129
	v_mov_b32_e32 v133, 0x3c23d70a
	v_cndmask_b32_e64 v133, 1.0, v133, s[98:99]
	v_mul_f32_e32 v132, v132, v133
	v_mul_f32_e32 v135, 0x3e22f983, v132
	v_cos_f32_e32 v134, v135
	v_sin_f32_e32 v135, v135
	v_mul_f32_e32 v137, 0x3d4e2601, v132
	v_cos_f32_e32 v136, v137
	v_sin_f32_e32 v137, v137
	v_mul_f32_e32 v131, 0x3c826136, v132
	v_cos_f32_e32 v130, v131
	v_sin_f32_e32 v131, v131
	v_mul_f32_e32 v133, 0x3ba4eb34, v132
	v_cos_f32_e32 v132, v133
	v_sin_f32_e32 v133, v133
	s_nop 0
	s_waitcnt vmcnt(0)
	v_mov_b32_e32 v180, v135
	v_mov_b32_e32 v181, v136
	v_mov_b32_e32 v135, v137
	v_mov_b32_e32 v136, v131
	v_mov_b32_e32 v137, v132
	v_mov_b32_e32 v131, v133
.LBB0_252:
	v_pk_mul_f32 v[132:133], v[126:127], v[126:127]
	v_pk_mul_f32 v[162:163], v[124:125], v[124:125]
	v_readlane_b32 s0, v252, 52
	v_pk_mov_b32 v[164:165], v[162:163], v[132:133] op_sel:[1,0]
	v_mov_b32_e32 v163, v133
	v_pk_add_f32 v[132:133], v[164:165], v[162:163]
	v_pk_mul_f32 v[162:163], v[122:123], v[122:123]
	v_pk_mul_f32 v[164:165], v[120:121], v[120:121]
	v_mov_b32_e32 v166, v162
	v_mov_b32_e32 v167, v164
	v_mov_b32_e32 v164, v163
	v_pk_add_f32 v[162:163], v[166:167], v[164:165]
	v_add_f32_e32 v129, v132, v133
	v_mbcnt_lo_u32_b32 v132, -1, 0
	v_mbcnt_hi_u32_b32 v132, -1, v132
	v_add_f32_e32 v129, v129, v163
	v_lshlrev_b32_e32 v132, 2, v132
	v_add_f32_e32 v129, v162, v129
	v_xor_b32_e32 v132, 64, v132
	ds_bpermute_b32 v132, v132, v129
	v_readlane_b32 s1, v252, 53
	v_ashrrev_i32_e32 v151, 31, v150
	v_mov_b32_e32 v194, v180
	v_mov_b32_e32 v195, v135
	s_waitcnt lgkmcnt(0)
	v_add_f32_e32 v129, v129, v132
	v_mbcnt_lo_u32_b32 v132, -1, 0
	v_mbcnt_hi_u32_b32 v132, -1, v132
	v_mov_b32_e32 v172, v134
	v_lshlrev_b32_e32 v132, 2, v132
	v_xor_b32_e32 v132, 0x80, v132
	ds_bpermute_b32 v162, v132, v129
	v_mov_b32_e32 v132, 0x3e8293ee
	v_cndmask_b32_e32 v176, 1.0, v132, vcc
	v_mov_b64_e32 v[132:133], s[0:1]
	v_mad_i64_i32 v[132:133], s[0:1], v184, s71, v[132:133]
	s_waitcnt lgkmcnt(0)
	v_add_f32_e32 v129, v129, v162
	v_fmamk_f32 v129, v129, 0x3d000000, v208
	v_rsq_f32_e32 v162, v129
	v_lshl_add_u64 v[164:165], v[150:151], 1, v[132:133]
	v_mov_b32_e32 v173, v181
	v_mov_b32_e32 v198, v136
	v_pk_mul_f32 v[132:133], v[126:127], v[162:163] op_sel_hi:[1,0]
	v_pk_mul_f32 v[166:167], v[124:125], v[162:163] op_sel_hi:[1,0]
	v_pk_mul_f32 v[168:169], v[122:123], v[162:163] op_sel_hi:[1,0]
	v_pk_mul_f32 v[162:163], v[120:121], v[162:163] op_sel_hi:[1,0]
	v_mov_b32_e32 v170, v166
	v_mov_b32_e32 v171, v163
	v_mov_b32_e32 v163, v167
	s_waitcnt vmcnt(0)
	v_pk_mul_f32 v[162:163], v[158:159], v[162:163]
	v_pk_mul_f32 v[170:171], v[174:175], v[170:171]
	v_pk_mul_f32 v[166:167], v[134:135], v[162:163]
	v_mov_b32_e32 v186, v170
	v_pk_fma_f32 v[166:167], v[180:181], v[170:171], v[166:167]
	v_mov_b32_e32 v187, v163
	v_mov_b32_e32 v163, v171
	v_mov_b32_e32 v170, v132
	v_mov_b32_e32 v171, v169
	v_mov_b32_e32 v169, v133
	v_pk_mul_f32 v[162:163], v[194:195], v[162:163]
	v_pk_mul_f32 v[170:171], v[156:157], v[170:171]
	v_pk_mul_f32 v[132:133], v[154:155], v[168:169]
	v_pk_fma_f32 v[162:163], v[172:173], v[186:187], v[162:163] neg_lo:[0,0,1] neg_hi:[0,0,1]
	v_pk_mul_f32 v[168:169], v[130:131], v[132:133]
	v_mov_b32_e32 v187, v133
	v_mov_b32_e32 v199, v131
	v_mov_b32_e32 v133, v171
	v_mov_b32_e32 v196, v130
	v_mov_b32_e32 v197, v137
	v_mov_b32_e32 v186, v170
	v_pk_mul_f32 v[132:133], v[198:199], v[132:133]
	v_pk_mul_f32 v[162:163], v[176:177], v[162:163] op_sel_hi:[0,1]
	v_pk_fma_f32 v[132:133], v[196:197], v[186:187], v[132:133] neg_lo:[0,0,1] neg_hi:[0,0,1]
	v_pk_mul_f32 v[166:167], v[176:177], v[166:167] op_sel_hi:[0,1]
	v_pk_mul_f32 v[132:133], v[176:177], v[132:133] op_sel_hi:[0,1]
	v_cvt_pk_bf16_f32 v190, v162, v163
	v_cvt_pk_bf16_f32 v191, v132, v133
	v_pk_mul_f32 v[132:133], v[118:119], v[118:119]
	v_pk_mul_f32 v[162:163], v[116:117], v[116:117]
	v_pk_fma_f32 v[168:169], v[136:137], v[170:171], v[168:169]
	v_cvt_pk_bf16_f32 v192, v166, v167
	v_pk_mov_b32 v[166:167], v[162:163], v[132:133] op_sel:[1,0]
	v_mov_b32_e32 v163, v133
	v_pk_mul_f32 v[168:169], v[176:177], v[168:169] op_sel_hi:[0,1]
	v_pk_add_f32 v[132:133], v[166:167], v[162:163]
	v_pk_mul_f32 v[162:163], v[114:115], v[114:115]
	v_pk_mul_f32 v[166:167], v[112:113], v[112:113]
	v_cvt_pk_bf16_f32 v193, v168, v169
	v_mov_b32_e32 v168, v162
	v_mov_b32_e32 v169, v166
	v_mov_b32_e32 v166, v163
	global_store_dwordx4 v[164:165], v[190:193], off
	v_pk_add_f32 v[162:163], v[168:169], v[166:167]
	v_add_f32_e32 v129, v132, v133
	v_mbcnt_lo_u32_b32 v132, -1, 0
	v_mbcnt_hi_u32_b32 v132, -1, v132
	v_add_f32_e32 v129, v129, v163
	v_lshlrev_b32_e32 v132, 2, v132
	v_add_f32_e32 v129, v162, v129
	v_xor_b32_e32 v132, 64, v132
	ds_bpermute_b32 v132, v132, v129
	s_andn2_b64 vcc, exec, s[22:23]
	v_mov_b32_e32 v179, 1.0
	s_waitcnt lgkmcnt(0)
	v_add_f32_e32 v129, v129, v132
	v_mbcnt_lo_u32_b32 v132, -1, 0
	v_mbcnt_hi_u32_b32 v132, -1, v132
	s_nop 0
	v_lshlrev_b32_e32 v132, 2, v132
	v_xor_b32_e32 v132, 0x80, v132
	ds_bpermute_b32 v132, v132, v129
	s_waitcnt lgkmcnt(0)
	v_add_f32_e32 v129, v129, v132
	v_fmamk_f32 v129, v129, 0x3d000000, v208
	v_rsq_f32_e32 v132, v129
	v_add_u32_e32 v129, 16, v185
	v_and_b32_e32 v186, 63, v129
	v_cndmask_b32_e64 v129, 0, 1, s[22:23]
	v_pk_mul_f32 v[162:163], v[118:119], v[132:133] op_sel_hi:[1,0]
	v_pk_mul_f32 v[166:167], v[116:117], v[132:133] op_sel_hi:[1,0]
	v_pk_mul_f32 v[168:169], v[114:115], v[132:133] op_sel_hi:[1,0]
	v_pk_mul_f32 v[132:133], v[112:113], v[132:133] op_sel_hi:[1,0]
	v_mov_b32_e32 v170, v166
	v_mov_b32_e32 v171, v133
	v_mov_b32_e32 v133, v167
	v_pk_mul_f32 v[170:171], v[174:175], v[170:171]
	v_pk_mul_f32 v[132:133], v[158:159], v[132:133]
	v_mov_b32_e32 v166, v170
	v_pk_mul_f32 v[134:135], v[134:135], v[132:133]
	v_mov_b32_e32 v167, v133
	v_mov_b32_e32 v133, v171
	v_pk_mul_f32 v[132:133], v[194:195], v[132:133]
	v_pk_fma_f32 v[134:135], v[180:181], v[170:171], v[134:135]
	v_pk_fma_f32 v[132:133], v[172:173], v[166:167], v[132:133] neg_lo:[0,0,1] neg_hi:[0,0,1]
	v_mov_b32_e32 v167, v169
	v_mov_b32_e32 v169, v163
	v_mov_b32_e32 v166, v162
	v_pk_mul_f32 v[162:163], v[154:155], v[168:169]
	v_pk_mul_f32 v[166:167], v[156:157], v[166:167]
	v_pk_mul_f32 v[130:131], v[130:131], v[162:163]
	v_pk_mul_f32 v[134:135], v[176:177], v[134:135] op_sel_hi:[0,1]
	v_pk_fma_f32 v[130:131], v[136:137], v[166:167], v[130:131]
	v_pk_mul_f32 v[132:133], v[176:177], v[132:133] op_sel_hi:[0,1]
	v_pk_mul_f32 v[136:137], v[176:177], v[130:131] op_sel_hi:[0,1]
	v_mov_b32_e32 v131, v163
	v_mov_b32_e32 v163, v167
	v_mov_b32_e32 v130, v166
	v_pk_mul_f32 v[162:163], v[198:199], v[162:163]
	v_cmp_ne_u32_e64 s[0:1], 1, v129
	v_pk_fma_f32 v[130:131], v[196:197], v[130:131], v[162:163] neg_lo:[0,0,1] neg_hi:[0,0,1]
	v_mov_b32_e32 v129, 0
	v_pk_mul_f32 v[162:163], v[176:177], v[130:131] op_sel_hi:[0,1]
	v_cvt_pk_bf16_f32 v130, v132, v133
	v_cvt_pk_bf16_f32 v131, v162, v163
	v_cvt_pk_bf16_f32 v132, v134, v135
	v_cvt_pk_bf16_f32 v133, v136, v137
	global_store_dwordx4 v[164:165], v[130:133], off offset:64
	v_add_u32_e32 v136, 16, v184
	s_nop 0
	v_mov_b32_e32 v132, 1.0
	v_mov_b32_e32 v130, 0
	v_mov_b32_e32 v131, 1.0
	v_mov_b32_e32 v133, 0
	s_cbranch_vccnz .LBB0_254
	v_bfe_u32 v128, v136, 6, 7
	v_cndmask_b32_e64 v128, v186, v128, s[42:43]
	v_cmp_ne_u32_e64 s[98:99], 0, v153
	v_cvt_f32_u32_e32 v134, v128
	v_mov_b32_e32 v135, 0x3c23d70a
	v_cndmask_b32_e64 v135, 1.0, v135, s[98:99]
	v_mul_f32_e32 v134, v134, v135
	v_mul_f32_e32 v129, 0x3e22f983, v134
	v_cos_f32_e32 v128, v129
	v_sin_f32_e32 v129, v129
	v_mul_f32_e32 v131, 0x3d4e2601, v134
	v_cos_f32_e32 v130, v131
	v_sin_f32_e32 v131, v131
	v_mul_f32_e32 v133, 0x3c826136, v134
	v_cos_f32_e32 v132, v133
	v_sin_f32_e32 v133, v133
	v_mul_f32_e32 v135, 0x3ba4eb34, v134
	v_cos_f32_e32 v134, v135
	v_sin_f32_e32 v135, v135
	s_nop 0
	v_mov_b32_e32 v178, v129
	v_mov_b32_e32 v179, v130
	v_mov_b32_e32 v129, v131
	v_mov_b32_e32 v130, v133
	v_mov_b32_e32 v131, v134
	v_mov_b32_e32 v133, v135
.LBB0_254:
	v_pk_mul_f32 v[134:135], v[110:111], v[110:111]
	v_pk_mul_f32 v[162:163], v[108:109], v[108:109]
	v_readlane_b32 s22, v252, 52
	v_pk_mov_b32 v[164:165], v[162:163], v[134:135] op_sel:[1,0]
	v_mov_b32_e32 v163, v135
	v_pk_add_f32 v[134:135], v[164:165], v[162:163]
	v_pk_mul_f32 v[162:163], v[106:107], v[106:107]
	v_pk_mul_f32 v[164:165], v[104:105], v[104:105]
	v_mov_b32_e32 v166, v162
	v_mov_b32_e32 v167, v164
	v_mov_b32_e32 v164, v163
	v_pk_add_f32 v[162:163], v[166:167], v[164:165]
	v_add_f32_e32 v134, v134, v135
	v_mbcnt_lo_u32_b32 v135, -1, 0
	v_mbcnt_hi_u32_b32 v135, -1, v135
	v_add_f32_e32 v134, v134, v163
	v_lshlrev_b32_e32 v135, 2, v135
	v_add_f32_e32 v134, v162, v134
	v_xor_b32_e32 v135, 64, v135
	ds_bpermute_b32 v135, v135, v134
	v_readlane_b32 s23, v252, 53
	v_mov_b32_e32 v180, v178
	v_mov_b32_e32 v181, v129
	v_mov_b32_e32 v170, v128
	s_waitcnt lgkmcnt(0)
	v_add_f32_e32 v137, v134, v135
	v_mbcnt_lo_u32_b32 v134, -1, 0
	v_mbcnt_hi_u32_b32 v134, -1, v134
	v_mov_b32_e32 v171, v179
	v_lshlrev_b32_e32 v134, 2, v134
	v_xor_b32_e32 v134, 0x80, v134
	ds_bpermute_b32 v162, v134, v137
	v_mov_b64_e32 v[134:135], s[22:23]
	v_mad_i64_i32 v[134:135], s[22:23], v136, s71, v[134:135]
	v_lshl_add_u64 v[164:165], v[150:151], 1, v[134:135]
	s_waitcnt lgkmcnt(0)
	v_add_f32_e32 v137, v137, v162
	v_fmamk_f32 v137, v137, 0x3d000000, v208
	v_rsq_f32_e32 v162, v137
	v_mov_b32_e32 v192, v130
	v_mov_b32_e32 v193, v133
	v_mov_b32_e32 v177, v176
	v_pk_mul_f32 v[134:135], v[110:111], v[162:163] op_sel_hi:[1,0]
	v_pk_mul_f32 v[136:137], v[108:109], v[162:163] op_sel_hi:[1,0]
	v_pk_mul_f32 v[166:167], v[106:107], v[162:163] op_sel_hi:[1,0]
	v_pk_mul_f32 v[162:163], v[104:105], v[162:163] op_sel_hi:[1,0]
	v_mov_b32_e32 v168, v136
	v_mov_b32_e32 v169, v163
	v_mov_b32_e32 v163, v137
	v_pk_mul_f32 v[136:137], v[158:159], v[162:163]
	v_pk_mul_f32 v[168:169], v[174:175], v[168:169]
	v_pk_mul_f32 v[162:163], v[128:129], v[136:137]
	v_mov_b32_e32 v172, v168
	v_pk_fma_f32 v[162:163], v[178:179], v[168:169], v[162:163]
	v_mov_b32_e32 v173, v137
	v_mov_b32_e32 v137, v169
	v_mov_b32_e32 v168, v134
	v_mov_b32_e32 v169, v167
	v_mov_b32_e32 v167, v135
	v_pk_mul_f32 v[168:169], v[156:157], v[168:169]
	v_pk_mul_f32 v[134:135], v[154:155], v[166:167]
	v_pk_mul_f32 v[136:137], v[180:181], v[136:137]
	v_pk_mul_f32 v[166:167], v[132:133], v[134:135]
	v_mov_b32_e32 v191, v135
	v_mov_b32_e32 v135, v169
	v_pk_fma_f32 v[136:137], v[170:171], v[172:173], v[136:137] neg_lo:[0,0,1] neg_hi:[0,0,1]
	v_mov_b32_e32 v172, v132
	v_mov_b32_e32 v173, v131
	v_mov_b32_e32 v190, v168
	v_pk_mul_f32 v[134:135], v[192:193], v[134:135]
	v_pk_fma_f32 v[166:167], v[130:131], v[168:169], v[166:167]
	v_pk_fma_f32 v[134:135], v[172:173], v[190:191], v[134:135] neg_lo:[0,0,1] neg_hi:[0,0,1]
	v_pk_mul_f32 v[162:163], v[176:177], v[162:163]
	v_pk_mul_f32 v[136:137], v[176:177], v[136:137]
	v_pk_mul_f32 v[166:167], v[176:177], v[166:167]
	v_pk_mul_f32 v[168:169], v[176:177], v[134:135]
	v_cvt_pk_bf16_f32 v134, v136, v137
	v_cvt_pk_bf16_f32 v135, v168, v169
	v_cvt_pk_bf16_f32 v136, v162, v163
	v_cvt_pk_bf16_f32 v137, v166, v167
	global_store_dwordx4 v[164:165], v[134:137], off
	v_xor_b32_e32 v187, 32, v189
	s_and_b64 vcc, exec, s[0:1]
	v_pk_mul_f32 v[134:135], v[102:103], v[102:103]
	v_pk_mul_f32 v[136:137], v[100:101], v[100:101]
	s_nop 0
	v_pk_mov_b32 v[162:163], v[136:137], v[134:135] op_sel:[1,0]
	v_mov_b32_e32 v137, v135
	v_pk_add_f32 v[134:135], v[162:163], v[136:137]
	v_pk_mul_f32 v[136:137], v[98:99], v[98:99]
	v_pk_mul_f32 v[162:163], v[96:97], v[96:97]
	v_mov_b32_e32 v166, v136
	v_mov_b32_e32 v167, v162
	v_mov_b32_e32 v162, v137
	v_pk_add_f32 v[136:137], v[166:167], v[162:163]
	v_add_f32_e32 v134, v134, v135
	v_mbcnt_lo_u32_b32 v135, -1, 0
	v_mbcnt_hi_u32_b32 v135, -1, v135
	v_add_f32_e32 v134, v134, v137
	v_lshlrev_b32_e32 v135, 2, v135
	v_add_f32_e32 v134, v136, v134
	v_xor_b32_e32 v135, 64, v135
	ds_bpermute_b32 v135, v135, v134
	s_waitcnt lgkmcnt(0)
	v_add_f32_e32 v134, v134, v135
	v_mbcnt_lo_u32_b32 v135, -1, 0
	v_mbcnt_hi_u32_b32 v135, -1, v135
	s_nop 0
	v_lshlrev_b32_e32 v135, 2, v135
	v_xor_b32_e32 v135, 0x80, v135
	ds_bpermute_b32 v135, v135, v134
	s_waitcnt lgkmcnt(0)
	v_add_f32_e32 v134, v134, v135
	v_fmamk_f32 v134, v134, 0x3d000000, v208
	v_rsq_f32_e32 v134, v134
	s_nop 0
	v_pk_mul_f32 v[136:137], v[102:103], v[134:135] op_sel_hi:[1,0]
	v_pk_mul_f32 v[162:163], v[100:101], v[134:135] op_sel_hi:[1,0]
	v_pk_mul_f32 v[166:167], v[98:99], v[134:135] op_sel_hi:[1,0]
	v_pk_mul_f32 v[134:135], v[96:97], v[134:135] op_sel_hi:[1,0]
	v_mov_b32_e32 v168, v162
	v_mov_b32_e32 v169, v135
	v_mov_b32_e32 v135, v163
	v_pk_mul_f32 v[134:135], v[158:159], v[134:135]
	v_pk_mul_f32 v[168:169], v[174:175], v[168:169]
	v_pk_mul_f32 v[128:129], v[128:129], v[134:135]
	s_nop 0
	v_pk_fma_f32 v[128:129], v[178:179], v[168:169], v[128:129]
	v_mov_b32_e32 v178, 0
	v_pk_mul_f32 v[162:163], v[176:177], v[128:129]
	v_mov_b32_e32 v129, v135
	v_mov_b32_e32 v135, v169
	v_mov_b32_e32 v128, v168
	v_pk_mul_f32 v[134:135], v[180:181], v[134:135]
	v_mov_b32_e32 v180, 0
	v_pk_fma_f32 v[128:129], v[170:171], v[128:129], v[134:135] neg_lo:[0,0,1] neg_hi:[0,0,1]
	v_mov_b32_e32 v135, v167
	v_mov_b32_e32 v167, v137
	v_mov_b32_e32 v134, v136
	v_pk_mul_f32 v[136:137], v[154:155], v[166:167]
	v_pk_mul_f32 v[134:135], v[156:157], v[134:135]
	v_pk_mul_f32 v[132:133], v[132:133], v[136:137]
	v_pk_mul_f32 v[128:129], v[176:177], v[128:129]
	v_pk_fma_f32 v[130:131], v[130:131], v[134:135], v[132:133]
	v_cvt_pk_bf16_f32 v128, v128, v129
	v_pk_mul_f32 v[132:133], v[176:177], v[130:131]
	v_mov_b32_e32 v131, v137
	v_mov_b32_e32 v137, v135
	v_mov_b32_e32 v130, v134
	v_pk_mul_f32 v[134:135], v[192:193], v[136:137]
	v_mov_b32_e32 v181, 1.0
	v_pk_fma_f32 v[130:131], v[172:173], v[130:131], v[134:135] neg_lo:[0,0,1] neg_hi:[0,0,1]
	v_mov_b32_e32 v134, 1.0
	v_pk_mul_f32 v[130:131], v[176:177], v[130:131]
	v_mov_b32_e32 v135, 0
	v_cvt_pk_bf16_f32 v129, v130, v131
	v_cvt_pk_bf16_f32 v130, v162, v163
	v_cvt_pk_bf16_f32 v131, v132, v133
	global_store_dwordx4 v[164:165], v[128:131], off offset:64
	v_mov_b32_e32 v136, 0
	v_mov_b32_e32 v137, 1.0
	v_add_u32_e32 v129, 32, v184
	v_mov_b32_e32 v128, 1.0
	v_mov_b32_e32 v130, 1.0
	v_mov_b32_e32 v131, 0
	s_cbranch_vccnz .LBB0_256
	v_bfe_u32 v130, v129, 6, 7
	v_cndmask_b32_e64 v130, v187, v130, s[42:43]
	v_cmp_ne_u32_e64 s[98:99], 0, v153
	v_cvt_f32_u32_e32 v132, v130
	v_mov_b32_e32 v133, 0x3c23d70a
	v_cndmask_b32_e64 v133, 1.0, v133, s[98:99]
	v_mul_f32_e32 v132, v132, v133
	v_mul_f32_e32 v135, 0x3e22f983, v132
	v_cos_f32_e32 v134, v135
	v_sin_f32_e32 v135, v135
	v_mul_f32_e32 v137, 0x3d4e2601, v132
	v_cos_f32_e32 v136, v137
	v_sin_f32_e32 v137, v137
	v_mul_f32_e32 v131, 0x3c826136, v132
	v_cos_f32_e32 v130, v131
	v_sin_f32_e32 v131, v131
	v_mul_f32_e32 v133, 0x3ba4eb34, v132
	v_cos_f32_e32 v132, v133
	v_sin_f32_e32 v133, v133
	s_nop 0
	v_mov_b32_e32 v180, v135
	v_mov_b32_e32 v181, v136
	v_mov_b32_e32 v135, v137
	v_mov_b32_e32 v136, v131
	v_mov_b32_e32 v137, v132
	v_mov_b32_e32 v131, v133
.LBB0_256:
	v_pk_mul_f32 v[132:133], v[94:95], v[94:95]
	v_pk_mul_f32 v[162:163], v[92:93], v[92:93]
	v_readlane_b32 s22, v252, 52
	v_pk_mov_b32 v[164:165], v[162:163], v[132:133] op_sel:[1,0]
	v_mov_b32_e32 v163, v133
	v_pk_add_f32 v[132:133], v[164:165], v[162:163]
	v_pk_mul_f32 v[162:163], v[90:91], v[90:91]
	v_pk_mul_f32 v[164:165], v[88:89], v[88:89]
	v_mov_b32_e32 v166, v162
	v_mov_b32_e32 v167, v164
	v_mov_b32_e32 v164, v163
	v_pk_add_f32 v[162:163], v[166:167], v[164:165]
	v_add_f32_e32 v132, v132, v133
	v_mbcnt_lo_u32_b32 v133, -1, 0
	v_mbcnt_hi_u32_b32 v133, -1, v133
	v_add_f32_e32 v132, v132, v163
	v_lshlrev_b32_e32 v133, 2, v133
	v_add_f32_e32 v132, v162, v132
	v_xor_b32_e32 v133, 64, v133
	ds_bpermute_b32 v133, v133, v132
	v_readlane_b32 s23, v252, 53
	v_mov_b32_e32 v194, v180
	v_mov_b32_e32 v195, v135
	v_mov_b32_e32 v172, v134
	s_waitcnt lgkmcnt(0)
	v_add_f32_e32 v162, v132, v133
	v_mbcnt_lo_u32_b32 v132, -1, 0
	v_mbcnt_hi_u32_b32 v132, -1, v132
	v_mov_b32_e32 v173, v181
	v_lshlrev_b32_e32 v132, 2, v132
	v_xor_b32_e32 v132, 0x80, v132
	ds_bpermute_b32 v163, v132, v162
	v_mov_b64_e32 v[132:133], s[22:23]
	v_mad_i64_i32 v[132:133], s[22:23], v129, s71, v[132:133]
	v_lshl_add_u64 v[164:165], v[150:151], 1, v[132:133]
	s_waitcnt lgkmcnt(0)
	v_add_f32_e32 v162, v162, v163
	v_fmamk_f32 v162, v162, 0x3d000000, v208
	v_rsq_f32_e32 v162, v162
	v_mov_b32_e32 v198, v136
	v_mov_b32_e32 v199, v131
	v_mov_b32_e32 v196, v130
	v_pk_mul_f32 v[132:133], v[94:95], v[162:163] op_sel_hi:[1,0]
	v_pk_mul_f32 v[166:167], v[92:93], v[162:163] op_sel_hi:[1,0]
	v_pk_mul_f32 v[168:169], v[90:91], v[162:163] op_sel_hi:[1,0]
	v_pk_mul_f32 v[162:163], v[88:89], v[162:163] op_sel_hi:[1,0]
	v_mov_b32_e32 v170, v166
	v_mov_b32_e32 v171, v163
	v_mov_b32_e32 v163, v167
	v_pk_mul_f32 v[162:163], v[158:159], v[162:163]
	v_pk_mul_f32 v[170:171], v[174:175], v[170:171]
	v_pk_mul_f32 v[166:167], v[134:135], v[162:163]
	v_mov_b32_e32 v190, v170
	v_pk_fma_f32 v[166:167], v[180:181], v[170:171], v[166:167]
	v_mov_b32_e32 v191, v163
	v_mov_b32_e32 v163, v171
	v_mov_b32_e32 v170, v132
	v_mov_b32_e32 v171, v169
	v_mov_b32_e32 v169, v133
	v_pk_mul_f32 v[162:163], v[194:195], v[162:163]
	v_pk_mul_f32 v[170:171], v[156:157], v[170:171]
	v_pk_mul_f32 v[132:133], v[154:155], v[168:169]
	v_pk_fma_f32 v[162:163], v[172:173], v[190:191], v[162:163] neg_lo:[0,0,1] neg_hi:[0,0,1]
	v_pk_mul_f32 v[168:169], v[130:131], v[132:133]
	v_mov_b32_e32 v191, v133
	v_mov_b32_e32 v133, v171
	v_mov_b32_e32 v197, v137
	v_mov_b32_e32 v190, v170
	v_pk_mul_f32 v[132:133], v[198:199], v[132:133]
	v_pk_mul_f32 v[162:163], v[176:177], v[162:163]
	v_pk_fma_f32 v[132:133], v[196:197], v[190:191], v[132:133] neg_lo:[0,0,1] neg_hi:[0,0,1]
	v_pk_mul_f32 v[166:167], v[176:177], v[166:167]
	v_pk_mul_f32 v[132:133], v[176:177], v[132:133]
	v_cvt_pk_bf16_f32 v190, v162, v163
	v_cvt_pk_bf16_f32 v191, v132, v133
	v_pk_mul_f32 v[132:133], v[86:87], v[86:87]
	v_pk_mul_f32 v[162:163], v[84:85], v[84:85]
	v_pk_fma_f32 v[168:169], v[136:137], v[170:171], v[168:169]
	v_cvt_pk_bf16_f32 v192, v166, v167
	v_pk_mov_b32 v[166:167], v[162:163], v[132:133] op_sel:[1,0]
	v_mov_b32_e32 v163, v133
	v_pk_mul_f32 v[168:169], v[176:177], v[168:169]
	v_pk_add_f32 v[132:133], v[166:167], v[162:163]
	v_pk_mul_f32 v[162:163], v[82:83], v[82:83]
	v_pk_mul_f32 v[166:167], v[80:81], v[80:81]
	v_cvt_pk_bf16_f32 v193, v168, v169
	v_mov_b32_e32 v168, v162
	v_mov_b32_e32 v169, v166
	v_mov_b32_e32 v166, v163
	global_store_dwordx4 v[164:165], v[190:193], off
	v_pk_add_f32 v[162:163], v[168:169], v[166:167]
	v_add_f32_e32 v129, v132, v133
	v_mbcnt_lo_u32_b32 v132, -1, 0
	v_mbcnt_hi_u32_b32 v132, -1, v132
	v_add_f32_e32 v129, v129, v163
	v_lshlrev_b32_e32 v132, 2, v132
	v_add_f32_e32 v129, v162, v129
	v_xor_b32_e32 v132, 64, v132
	ds_bpermute_b32 v132, v132, v129
	s_and_b64 vcc, exec, s[0:1]
	v_mov_b32_e32 v179, 1.0
	s_waitcnt lgkmcnt(0)
	v_add_f32_e32 v129, v129, v132
	v_mbcnt_lo_u32_b32 v132, -1, 0
	v_mbcnt_hi_u32_b32 v132, -1, v132
	s_nop 0
	v_lshlrev_b32_e32 v132, 2, v132
	v_xor_b32_e32 v132, 0x80, v132
	ds_bpermute_b32 v132, v132, v129
	s_waitcnt lgkmcnt(0)
	v_add_f32_e32 v129, v129, v132
	v_fmamk_f32 v129, v129, 0x3d000000, v208
	v_rsq_f32_e32 v132, v129
	v_add_u32_e32 v129, 48, v185
	v_and_b32_e32 v188, 63, v129
	v_mov_b32_e32 v129, 0
	v_pk_mul_f32 v[162:163], v[86:87], v[132:133] op_sel_hi:[1,0]
	v_pk_mul_f32 v[166:167], v[84:85], v[132:133] op_sel_hi:[1,0]
	v_pk_mul_f32 v[168:169], v[82:83], v[132:133] op_sel_hi:[1,0]
	v_pk_mul_f32 v[132:133], v[80:81], v[132:133] op_sel_hi:[1,0]
	v_mov_b32_e32 v170, v166
	v_mov_b32_e32 v171, v133
	v_mov_b32_e32 v133, v167
	v_pk_mul_f32 v[170:171], v[174:175], v[170:171]
	v_pk_mul_f32 v[132:133], v[158:159], v[132:133]
	v_mov_b32_e32 v166, v170
	v_pk_mul_f32 v[134:135], v[134:135], v[132:133]
	v_mov_b32_e32 v167, v133
	v_mov_b32_e32 v133, v171
	v_pk_mul_f32 v[132:133], v[194:195], v[132:133]
	v_pk_fma_f32 v[134:135], v[180:181], v[170:171], v[134:135]
	v_pk_fma_f32 v[132:133], v[172:173], v[166:167], v[132:133] neg_lo:[0,0,1] neg_hi:[0,0,1]
	v_mov_b32_e32 v167, v169
	v_mov_b32_e32 v169, v163
	v_mov_b32_e32 v166, v162
	v_pk_mul_f32 v[162:163], v[154:155], v[168:169]
	v_pk_mul_f32 v[166:167], v[156:157], v[166:167]
	v_pk_mul_f32 v[130:131], v[130:131], v[162:163]
	v_pk_mul_f32 v[134:135], v[176:177], v[134:135]
	v_pk_fma_f32 v[130:131], v[136:137], v[166:167], v[130:131]
	v_pk_mul_f32 v[132:133], v[176:177], v[132:133]
	v_pk_mul_f32 v[136:137], v[176:177], v[130:131]
	v_mov_b32_e32 v131, v163
	v_mov_b32_e32 v163, v167
	v_mov_b32_e32 v130, v166
	v_pk_mul_f32 v[162:163], v[198:199], v[162:163]
	s_nop 0
	v_pk_fma_f32 v[130:131], v[196:197], v[130:131], v[162:163] neg_lo:[0,0,1] neg_hi:[0,0,1]
	s_nop 0
	v_pk_mul_f32 v[162:163], v[176:177], v[130:131]
	v_cvt_pk_bf16_f32 v130, v132, v133
	v_cvt_pk_bf16_f32 v131, v162, v163
	v_cvt_pk_bf16_f32 v132, v134, v135
	v_cvt_pk_bf16_f32 v133, v136, v137
	global_store_dwordx4 v[164:165], v[130:133], off offset:64
	v_add_u32_e32 v136, 48, v184
	s_nop 0
	v_mov_b32_e32 v132, 1.0
	v_mov_b32_e32 v130, 0
	v_mov_b32_e32 v131, 1.0
	v_mov_b32_e32 v133, 0
	s_cbranch_vccnz .LBB0_258
	v_bfe_u32 v128, v136, 6, 7
	v_cndmask_b32_e64 v128, v188, v128, s[42:43]
	v_cmp_ne_u32_e64 s[98:99], 0, v153
	v_cvt_f32_u32_e32 v134, v128
	v_mov_b32_e32 v135, 0x3c23d70a
	v_cndmask_b32_e64 v135, 1.0, v135, s[98:99]
	v_mul_f32_e32 v134, v134, v135
	v_mul_f32_e32 v129, 0x3e22f983, v134
	v_cos_f32_e32 v128, v129
	v_sin_f32_e32 v129, v129
	v_mul_f32_e32 v131, 0x3d4e2601, v134
	v_cos_f32_e32 v130, v131
	v_sin_f32_e32 v131, v131
	v_mul_f32_e32 v133, 0x3c826136, v134
	v_cos_f32_e32 v132, v133
	v_sin_f32_e32 v133, v133
	v_mul_f32_e32 v135, 0x3ba4eb34, v134
	v_cos_f32_e32 v134, v135
	v_sin_f32_e32 v135, v135
	s_nop 0
	v_mov_b32_e32 v178, v129
	v_mov_b32_e32 v179, v130
	v_mov_b32_e32 v129, v131
	v_mov_b32_e32 v130, v133
	v_mov_b32_e32 v131, v134
	v_mov_b32_e32 v133, v135
.LBB0_258:
	v_pk_mul_f32 v[134:135], v[78:79], v[78:79]
	v_pk_mul_f32 v[162:163], v[76:77], v[76:77]
	v_readlane_b32 s22, v252, 52
	v_pk_mov_b32 v[164:165], v[162:163], v[134:135] op_sel:[1,0]
	v_mov_b32_e32 v163, v135
	v_pk_add_f32 v[134:135], v[164:165], v[162:163]
	v_pk_mul_f32 v[162:163], v[74:75], v[74:75]
	v_pk_mul_f32 v[164:165], v[72:73], v[72:73]
	v_mov_b32_e32 v166, v162
	v_mov_b32_e32 v167, v164
	v_mov_b32_e32 v164, v163
	v_pk_add_f32 v[162:163], v[166:167], v[164:165]
	v_add_f32_e32 v134, v134, v135
	v_mbcnt_lo_u32_b32 v135, -1, 0
	v_mbcnt_hi_u32_b32 v135, -1, v135
	v_add_f32_e32 v134, v134, v163
	v_lshlrev_b32_e32 v135, 2, v135
	v_add_f32_e32 v134, v162, v134
	v_xor_b32_e32 v135, 64, v135
	ds_bpermute_b32 v135, v135, v134
	v_readlane_b32 s23, v252, 53
	v_mov_b32_e32 v180, v178
	v_mov_b32_e32 v181, v129
	v_mov_b32_e32 v170, v128
	s_waitcnt lgkmcnt(0)
	v_add_f32_e32 v137, v134, v135
	v_mbcnt_lo_u32_b32 v134, -1, 0
	v_mbcnt_hi_u32_b32 v134, -1, v134
	v_mov_b32_e32 v171, v179
	v_lshlrev_b32_e32 v134, 2, v134
	v_xor_b32_e32 v134, 0x80, v134
	ds_bpermute_b32 v162, v134, v137
	v_mov_b64_e32 v[134:135], s[22:23]
	v_mad_i64_i32 v[134:135], s[22:23], v136, s71, v[134:135]
	v_lshl_add_u64 v[164:165], v[150:151], 1, v[134:135]
	s_waitcnt lgkmcnt(0)
	v_add_f32_e32 v137, v137, v162
	v_fmamk_f32 v137, v137, 0x3d000000, v208
	v_rsq_f32_e32 v162, v137
	v_mov_b32_e32 v192, v130
	v_mov_b32_e32 v193, v133
	s_and_b64 vcc, exec, s[0:1]
	v_pk_mul_f32 v[134:135], v[78:79], v[162:163] op_sel_hi:[1,0]
	v_pk_mul_f32 v[136:137], v[76:77], v[162:163] op_sel_hi:[1,0]
	v_pk_mul_f32 v[166:167], v[74:75], v[162:163] op_sel_hi:[1,0]
	v_pk_mul_f32 v[162:163], v[72:73], v[162:163] op_sel_hi:[1,0]
	v_mov_b32_e32 v168, v136
	v_mov_b32_e32 v169, v163
	v_mov_b32_e32 v163, v137
	v_pk_mul_f32 v[136:137], v[158:159], v[162:163]
	v_pk_mul_f32 v[168:169], v[174:175], v[168:169]
	v_pk_mul_f32 v[162:163], v[128:129], v[136:137]
	v_mov_b32_e32 v172, v168
	v_pk_fma_f32 v[162:163], v[178:179], v[168:169], v[162:163]
	v_mov_b32_e32 v173, v137
	v_mov_b32_e32 v137, v169
	v_mov_b32_e32 v168, v134
	v_mov_b32_e32 v169, v167
	v_mov_b32_e32 v167, v135
	v_pk_mul_f32 v[168:169], v[156:157], v[168:169]
	v_pk_mul_f32 v[134:135], v[154:155], v[166:167]
	v_pk_mul_f32 v[136:137], v[180:181], v[136:137]
	v_pk_mul_f32 v[166:167], v[132:133], v[134:135]
	v_mov_b32_e32 v191, v135
	v_mov_b32_e32 v135, v169
	v_pk_fma_f32 v[136:137], v[170:171], v[172:173], v[136:137] neg_lo:[0,0,1] neg_hi:[0,0,1]
	v_mov_b32_e32 v172, v132
	v_mov_b32_e32 v173, v131
	v_mov_b32_e32 v190, v168
	v_pk_mul_f32 v[134:135], v[192:193], v[134:135]
	v_pk_fma_f32 v[166:167], v[130:131], v[168:169], v[166:167]
	v_pk_fma_f32 v[134:135], v[172:173], v[190:191], v[134:135] neg_lo:[0,0,1] neg_hi:[0,0,1]
	v_pk_mul_f32 v[162:163], v[176:177], v[162:163]
	v_pk_mul_f32 v[136:137], v[176:177], v[136:137]
	v_pk_mul_f32 v[166:167], v[176:177], v[166:167]
	v_pk_mul_f32 v[168:169], v[176:177], v[134:135]
	v_cvt_pk_bf16_f32 v134, v136, v137
	v_cvt_pk_bf16_f32 v135, v168, v169
	v_cvt_pk_bf16_f32 v136, v162, v163
	v_cvt_pk_bf16_f32 v137, v166, v167
	global_store_dwordx4 v[164:165], v[134:137], off
	s_nop 1
	v_pk_mul_f32 v[134:135], v[70:71], v[70:71]
	v_pk_mul_f32 v[136:137], v[68:69], v[68:69]
	s_nop 0
	v_pk_mov_b32 v[162:163], v[136:137], v[134:135] op_sel:[1,0]
	v_mov_b32_e32 v137, v135
	v_pk_add_f32 v[134:135], v[162:163], v[136:137]
	v_pk_mul_f32 v[136:137], v[66:67], v[66:67]
	v_pk_mul_f32 v[162:163], v[64:65], v[64:65]
	v_mov_b32_e32 v166, v136
	v_mov_b32_e32 v167, v162
	v_mov_b32_e32 v162, v137
	v_pk_add_f32 v[136:137], v[166:167], v[162:163]
	v_add_f32_e32 v134, v134, v135
	v_mbcnt_lo_u32_b32 v135, -1, 0
	v_mbcnt_hi_u32_b32 v135, -1, v135
	v_add_f32_e32 v134, v134, v137
	v_lshlrev_b32_e32 v135, 2, v135
	v_add_f32_e32 v134, v136, v134
	v_xor_b32_e32 v135, 64, v135
	ds_bpermute_b32 v135, v135, v134
	s_waitcnt lgkmcnt(0)
	v_add_f32_e32 v134, v134, v135
	v_mbcnt_lo_u32_b32 v135, -1, 0
	v_mbcnt_hi_u32_b32 v135, -1, v135
	s_nop 0
	v_lshlrev_b32_e32 v135, 2, v135
	v_xor_b32_e32 v135, 0x80, v135
	ds_bpermute_b32 v135, v135, v134
	s_waitcnt lgkmcnt(0)
	v_add_f32_e32 v134, v134, v135
	v_fmamk_f32 v134, v134, 0x3d000000, v208
	v_rsq_f32_e32 v134, v134
	s_nop 0
	v_pk_mul_f32 v[136:137], v[70:71], v[134:135] op_sel_hi:[1,0]
	v_pk_mul_f32 v[162:163], v[68:69], v[134:135] op_sel_hi:[1,0]
	v_pk_mul_f32 v[166:167], v[66:67], v[134:135] op_sel_hi:[1,0]
	v_pk_mul_f32 v[134:135], v[64:65], v[134:135] op_sel_hi:[1,0]
	v_mov_b32_e32 v168, v162
	v_mov_b32_e32 v169, v135
	v_mov_b32_e32 v135, v163
	v_pk_mul_f32 v[134:135], v[158:159], v[134:135]
	v_pk_mul_f32 v[168:169], v[174:175], v[168:169]
	v_pk_mul_f32 v[128:129], v[128:129], v[134:135]
	s_nop 0
	v_pk_fma_f32 v[128:129], v[178:179], v[168:169], v[128:129]
	v_mov_b32_e32 v178, 0
	v_pk_mul_f32 v[162:163], v[176:177], v[128:129]
	v_mov_b32_e32 v129, v135
	v_mov_b32_e32 v135, v169
	v_mov_b32_e32 v128, v168
	v_pk_mul_f32 v[134:135], v[180:181], v[134:135]
	v_mov_b32_e32 v180, 0
	v_pk_fma_f32 v[128:129], v[170:171], v[128:129], v[134:135] neg_lo:[0,0,1] neg_hi:[0,0,1]
	v_mov_b32_e32 v135, v167
	v_mov_b32_e32 v167, v137
	v_mov_b32_e32 v134, v136
	v_pk_mul_f32 v[136:137], v[154:155], v[166:167]
	v_pk_mul_f32 v[134:135], v[156:157], v[134:135]
	v_pk_mul_f32 v[132:133], v[132:133], v[136:137]
	v_pk_mul_f32 v[128:129], v[176:177], v[128:129]
	v_pk_fma_f32 v[130:131], v[130:131], v[134:135], v[132:133]
	v_cvt_pk_bf16_f32 v128, v128, v129
	v_pk_mul_f32 v[132:133], v[176:177], v[130:131]
	v_mov_b32_e32 v131, v137
	v_mov_b32_e32 v137, v135
	v_mov_b32_e32 v130, v134
	v_pk_mul_f32 v[134:135], v[192:193], v[136:137]
	v_mov_b32_e32 v181, 1.0
	v_pk_fma_f32 v[130:131], v[172:173], v[130:131], v[134:135] neg_lo:[0,0,1] neg_hi:[0,0,1]
	v_mov_b32_e32 v134, 1.0
	v_pk_mul_f32 v[130:131], v[176:177], v[130:131]
	v_mov_b32_e32 v135, 0
	v_cvt_pk_bf16_f32 v129, v130, v131
	v_cvt_pk_bf16_f32 v130, v162, v163
	v_cvt_pk_bf16_f32 v131, v132, v133
	global_store_dwordx4 v[164:165], v[128:131], off offset:64
	v_mov_b32_e32 v136, 0
	v_mov_b32_e32 v137, 1.0
	v_add_u32_e32 v129, 0x80, v184
	v_mov_b32_e32 v128, 1.0
	v_mov_b32_e32 v130, 1.0
	v_mov_b32_e32 v131, 0
	s_cbranch_vccnz .LBB0_260
	v_bfe_u32 v130, v129, 6, 7
	v_cndmask_b32_e64 v130, v189, v130, s[42:43]
	v_cmp_ne_u32_e64 s[98:99], 0, v153
	v_cvt_f32_u32_e32 v132, v130
	v_mov_b32_e32 v133, 0x3c23d70a
	v_cndmask_b32_e64 v133, 1.0, v133, s[98:99]
	v_mul_f32_e32 v132, v132, v133
	v_mul_f32_e32 v135, 0x3e22f983, v132
	v_cos_f32_e32 v134, v135
	v_sin_f32_e32 v135, v135
	v_mul_f32_e32 v137, 0x3d4e2601, v132
	v_cos_f32_e32 v136, v137
	v_sin_f32_e32 v137, v137
	v_mul_f32_e32 v131, 0x3c826136, v132
	v_cos_f32_e32 v130, v131
	v_sin_f32_e32 v131, v131
	v_mul_f32_e32 v133, 0x3ba4eb34, v132
	v_cos_f32_e32 v132, v133
	v_sin_f32_e32 v133, v133
	s_nop 0
	v_mov_b32_e32 v180, v135
	v_mov_b32_e32 v181, v136
	v_mov_b32_e32 v135, v137
	v_mov_b32_e32 v136, v131
	v_mov_b32_e32 v137, v132
	v_mov_b32_e32 v131, v133
.LBB0_260:
	v_pk_mul_f32 v[132:133], v[62:63], v[62:63]
	v_pk_mul_f32 v[162:163], v[60:61], v[60:61]
	v_readlane_b32 s22, v252, 52
	v_pk_mov_b32 v[164:165], v[162:163], v[132:133] op_sel:[1,0]
	v_mov_b32_e32 v163, v133
	v_pk_add_f32 v[132:133], v[164:165], v[162:163]
	v_pk_mul_f32 v[162:163], v[58:59], v[58:59]
	v_pk_mul_f32 v[164:165], v[56:57], v[56:57]
	v_mov_b32_e32 v166, v162
	v_mov_b32_e32 v167, v164
	v_mov_b32_e32 v164, v163
	v_pk_add_f32 v[162:163], v[166:167], v[164:165]
	v_add_f32_e32 v132, v132, v133
	v_mbcnt_lo_u32_b32 v133, -1, 0
	v_mbcnt_hi_u32_b32 v133, -1, v133
	v_add_f32_e32 v132, v132, v163
	v_lshlrev_b32_e32 v133, 2, v133
	v_add_f32_e32 v132, v162, v132
	v_xor_b32_e32 v133, 64, v133
	ds_bpermute_b32 v133, v133, v132
	v_readlane_b32 s23, v252, 53
	v_mov_b32_e32 v194, v180
	v_mov_b32_e32 v195, v135
	v_mov_b32_e32 v172, v134
	s_waitcnt lgkmcnt(0)
	v_add_f32_e32 v162, v132, v133
	v_mbcnt_lo_u32_b32 v132, -1, 0
	v_mbcnt_hi_u32_b32 v132, -1, v132
	v_mov_b32_e32 v173, v181
	v_lshlrev_b32_e32 v132, 2, v132
	v_xor_b32_e32 v132, 0x80, v132
	ds_bpermute_b32 v163, v132, v162
	v_mov_b64_e32 v[132:133], s[22:23]
	v_mad_i64_i32 v[132:133], s[22:23], v129, s71, v[132:133]
	v_lshl_add_u64 v[164:165], v[150:151], 1, v[132:133]
	s_waitcnt lgkmcnt(0)
	v_add_f32_e32 v162, v162, v163
	v_fmamk_f32 v162, v162, 0x3d000000, v208
	v_rsq_f32_e32 v162, v162
	v_mov_b32_e32 v198, v136
	v_mov_b32_e32 v199, v131
	v_mov_b32_e32 v196, v130
	v_pk_mul_f32 v[132:133], v[62:63], v[162:163] op_sel_hi:[1,0]
	v_pk_mul_f32 v[166:167], v[60:61], v[162:163] op_sel_hi:[1,0]
	v_pk_mul_f32 v[168:169], v[58:59], v[162:163] op_sel_hi:[1,0]
	v_pk_mul_f32 v[162:163], v[56:57], v[162:163] op_sel_hi:[1,0]
	v_mov_b32_e32 v170, v166
	v_mov_b32_e32 v171, v163
	v_mov_b32_e32 v163, v167
	v_pk_mul_f32 v[162:163], v[158:159], v[162:163]
	v_pk_mul_f32 v[170:171], v[174:175], v[170:171]
	v_pk_mul_f32 v[166:167], v[134:135], v[162:163]
	v_mov_b32_e32 v190, v170
	v_pk_fma_f32 v[166:167], v[180:181], v[170:171], v[166:167]
	v_mov_b32_e32 v191, v163
	v_mov_b32_e32 v163, v171
	v_mov_b32_e32 v170, v132
	v_mov_b32_e32 v171, v169
	v_mov_b32_e32 v169, v133
	v_pk_mul_f32 v[162:163], v[194:195], v[162:163]
	v_pk_mul_f32 v[170:171], v[156:157], v[170:171]
	v_pk_mul_f32 v[132:133], v[154:155], v[168:169]
	v_pk_fma_f32 v[162:163], v[172:173], v[190:191], v[162:163] neg_lo:[0,0,1] neg_hi:[0,0,1]
	v_pk_mul_f32 v[168:169], v[130:131], v[132:133]
	v_mov_b32_e32 v191, v133
	v_mov_b32_e32 v133, v171
	v_mov_b32_e32 v197, v137
	v_mov_b32_e32 v190, v170
	v_pk_mul_f32 v[132:133], v[198:199], v[132:133]
	v_pk_mul_f32 v[162:163], v[176:177], v[162:163]
	v_pk_fma_f32 v[132:133], v[196:197], v[190:191], v[132:133] neg_lo:[0,0,1] neg_hi:[0,0,1]
	v_pk_mul_f32 v[166:167], v[176:177], v[166:167]
	v_pk_mul_f32 v[132:133], v[176:177], v[132:133]
	v_cvt_pk_bf16_f32 v190, v162, v163
	v_cvt_pk_bf16_f32 v191, v132, v133
	v_pk_mul_f32 v[132:133], v[54:55], v[54:55]
	v_pk_mul_f32 v[162:163], v[52:53], v[52:53]
	v_pk_fma_f32 v[168:169], v[136:137], v[170:171], v[168:169]
	v_cvt_pk_bf16_f32 v192, v166, v167
	v_pk_mov_b32 v[166:167], v[162:163], v[132:133] op_sel:[1,0]
	v_mov_b32_e32 v163, v133
	v_pk_mul_f32 v[168:169], v[176:177], v[168:169]
	v_pk_add_f32 v[132:133], v[166:167], v[162:163]
	v_pk_mul_f32 v[162:163], v[50:51], v[50:51]
	v_pk_mul_f32 v[166:167], v[48:49], v[48:49]
	v_cvt_pk_bf16_f32 v193, v168, v169
	v_mov_b32_e32 v168, v162
	v_mov_b32_e32 v169, v166
	v_mov_b32_e32 v166, v163
	global_store_dwordx4 v[164:165], v[190:193], off
	v_pk_add_f32 v[162:163], v[168:169], v[166:167]
	v_add_f32_e32 v129, v132, v133
	v_mbcnt_lo_u32_b32 v132, -1, 0
	v_mbcnt_hi_u32_b32 v132, -1, v132
	v_add_f32_e32 v129, v129, v163
	v_lshlrev_b32_e32 v132, 2, v132
	v_add_f32_e32 v129, v162, v129
	v_xor_b32_e32 v132, 64, v132
	ds_bpermute_b32 v132, v132, v129
	s_and_b64 vcc, exec, s[0:1]
	v_mov_b32_e32 v179, 1.0
	s_waitcnt lgkmcnt(0)
	v_add_f32_e32 v129, v129, v132
	v_mbcnt_lo_u32_b32 v132, -1, 0
	v_mbcnt_hi_u32_b32 v132, -1, v132
	s_nop 0
	v_lshlrev_b32_e32 v132, 2, v132
	v_xor_b32_e32 v132, 0x80, v132
	ds_bpermute_b32 v132, v132, v129
	s_waitcnt lgkmcnt(0)
	v_add_f32_e32 v129, v129, v132
	v_fmamk_f32 v129, v129, 0x3d000000, v208
	v_rsq_f32_e32 v132, v129
	v_mov_b32_e32 v129, 0
	v_pk_mul_f32 v[162:163], v[54:55], v[132:133] op_sel_hi:[1,0]
	v_pk_mul_f32 v[166:167], v[52:53], v[132:133] op_sel_hi:[1,0]
	v_pk_mul_f32 v[168:169], v[50:51], v[132:133] op_sel_hi:[1,0]
	v_pk_mul_f32 v[132:133], v[48:49], v[132:133] op_sel_hi:[1,0]
	v_mov_b32_e32 v170, v166
	v_mov_b32_e32 v171, v133
	v_mov_b32_e32 v133, v167
	v_pk_mul_f32 v[170:171], v[174:175], v[170:171]
	v_pk_mul_f32 v[132:133], v[158:159], v[132:133]
	v_mov_b32_e32 v166, v170
	v_pk_mul_f32 v[134:135], v[134:135], v[132:133]
	v_mov_b32_e32 v167, v133
	v_mov_b32_e32 v133, v171
	v_pk_mul_f32 v[132:133], v[194:195], v[132:133]
	v_pk_fma_f32 v[134:135], v[180:181], v[170:171], v[134:135]
	v_pk_fma_f32 v[132:133], v[172:173], v[166:167], v[132:133] neg_lo:[0,0,1] neg_hi:[0,0,1]
	v_mov_b32_e32 v167, v169
	v_mov_b32_e32 v169, v163
	v_mov_b32_e32 v166, v162
	v_pk_mul_f32 v[162:163], v[154:155], v[168:169]
	v_pk_mul_f32 v[166:167], v[156:157], v[166:167]
	v_pk_mul_f32 v[130:131], v[130:131], v[162:163]
	v_pk_mul_f32 v[134:135], v[176:177], v[134:135]
	v_pk_fma_f32 v[130:131], v[136:137], v[166:167], v[130:131]
	v_pk_mul_f32 v[132:133], v[176:177], v[132:133]
	v_pk_mul_f32 v[136:137], v[176:177], v[130:131]
	v_mov_b32_e32 v131, v163
	v_mov_b32_e32 v163, v167
	v_mov_b32_e32 v130, v166
	v_pk_mul_f32 v[162:163], v[198:199], v[162:163]
	s_nop 0
	v_pk_fma_f32 v[130:131], v[196:197], v[130:131], v[162:163] neg_lo:[0,0,1] neg_hi:[0,0,1]
	s_nop 0
	v_pk_mul_f32 v[162:163], v[176:177], v[130:131]
	v_cvt_pk_bf16_f32 v130, v132, v133
	v_cvt_pk_bf16_f32 v131, v162, v163
	v_cvt_pk_bf16_f32 v132, v134, v135
	v_cvt_pk_bf16_f32 v133, v136, v137
	global_store_dwordx4 v[164:165], v[130:133], off offset:64
	v_add_u32_e32 v136, 0x90, v184
	s_nop 0
	v_mov_b32_e32 v132, 1.0
	v_mov_b32_e32 v130, 0
	v_mov_b32_e32 v131, 1.0
	v_mov_b32_e32 v133, 0
	s_cbranch_vccnz .LBB0_262
	v_bfe_u32 v128, v136, 6, 7
	v_cndmask_b32_e64 v128, v186, v128, s[42:43]
	v_cmp_ne_u32_e64 s[98:99], 0, v153
	v_cvt_f32_u32_e32 v134, v128
	v_mov_b32_e32 v135, 0x3c23d70a
	v_cndmask_b32_e64 v135, 1.0, v135, s[98:99]
	v_mul_f32_e32 v134, v134, v135
	v_mul_f32_e32 v129, 0x3e22f983, v134
	v_cos_f32_e32 v128, v129
	v_sin_f32_e32 v129, v129
	v_mul_f32_e32 v131, 0x3d4e2601, v134
	v_cos_f32_e32 v130, v131
	v_sin_f32_e32 v131, v131
	v_mul_f32_e32 v133, 0x3c826136, v134
	v_cos_f32_e32 v132, v133
	v_sin_f32_e32 v133, v133
	v_mul_f32_e32 v135, 0x3ba4eb34, v134
	v_cos_f32_e32 v134, v135
	v_sin_f32_e32 v135, v135
	s_nop 0
	v_mov_b32_e32 v178, v129
	v_mov_b32_e32 v179, v130
	v_mov_b32_e32 v129, v131
	v_mov_b32_e32 v130, v133
	v_mov_b32_e32 v131, v134
	v_mov_b32_e32 v133, v135
.LBB0_262:
	v_pk_mul_f32 v[134:135], v[46:47], v[46:47]
	v_pk_mul_f32 v[162:163], v[44:45], v[44:45]
	v_readlane_b32 s22, v252, 52
	v_pk_mov_b32 v[164:165], v[162:163], v[134:135] op_sel:[1,0]
	v_mov_b32_e32 v163, v135
	v_pk_add_f32 v[134:135], v[164:165], v[162:163]
	v_pk_mul_f32 v[162:163], v[42:43], v[42:43]
	v_pk_mul_f32 v[164:165], v[40:41], v[40:41]
	v_mov_b32_e32 v166, v162
	v_mov_b32_e32 v167, v164
	v_mov_b32_e32 v164, v163
	v_pk_add_f32 v[162:163], v[166:167], v[164:165]
	v_add_f32_e32 v134, v134, v135
	v_mbcnt_lo_u32_b32 v135, -1, 0
	v_mbcnt_hi_u32_b32 v135, -1, v135
	v_add_f32_e32 v134, v134, v163
	v_lshlrev_b32_e32 v135, 2, v135
	v_add_f32_e32 v134, v162, v134
	v_xor_b32_e32 v135, 64, v135
	ds_bpermute_b32 v135, v135, v134
	v_readlane_b32 s23, v252, 53
	v_mov_b32_e32 v180, v178
	v_mov_b32_e32 v181, v129
	v_mov_b32_e32 v170, v128
	s_waitcnt lgkmcnt(0)
	v_add_f32_e32 v137, v134, v135
	v_mbcnt_lo_u32_b32 v134, -1, 0
	v_mbcnt_hi_u32_b32 v134, -1, v134
	v_mov_b32_e32 v171, v179
	v_lshlrev_b32_e32 v134, 2, v134
	v_xor_b32_e32 v134, 0x80, v134
	ds_bpermute_b32 v162, v134, v137
	v_mov_b64_e32 v[134:135], s[22:23]
	v_mad_i64_i32 v[134:135], s[22:23], v136, s71, v[134:135]
	v_lshl_add_u64 v[164:165], v[150:151], 1, v[134:135]
	s_waitcnt lgkmcnt(0)
	v_add_f32_e32 v137, v137, v162
	v_fmamk_f32 v137, v137, 0x3d000000, v208
	v_rsq_f32_e32 v162, v137
	v_mov_b32_e32 v192, v130
	v_mov_b32_e32 v193, v133
	s_and_b64 vcc, exec, s[0:1]
	v_pk_mul_f32 v[134:135], v[46:47], v[162:163] op_sel_hi:[1,0]
	v_pk_mul_f32 v[136:137], v[44:45], v[162:163] op_sel_hi:[1,0]
	v_pk_mul_f32 v[166:167], v[42:43], v[162:163] op_sel_hi:[1,0]
	v_pk_mul_f32 v[162:163], v[40:41], v[162:163] op_sel_hi:[1,0]
	v_mov_b32_e32 v168, v136
	v_mov_b32_e32 v169, v163
	v_mov_b32_e32 v163, v137
	v_pk_mul_f32 v[136:137], v[158:159], v[162:163]
	v_pk_mul_f32 v[168:169], v[174:175], v[168:169]
	v_pk_mul_f32 v[162:163], v[128:129], v[136:137]
	v_mov_b32_e32 v172, v168
	v_pk_fma_f32 v[162:163], v[178:179], v[168:169], v[162:163]
	v_mov_b32_e32 v173, v137
	v_mov_b32_e32 v137, v169
	v_mov_b32_e32 v168, v134
	v_mov_b32_e32 v169, v167
	v_mov_b32_e32 v167, v135
	v_pk_mul_f32 v[168:169], v[156:157], v[168:169]
	v_pk_mul_f32 v[134:135], v[154:155], v[166:167]
	v_pk_mul_f32 v[136:137], v[180:181], v[136:137]
	v_pk_mul_f32 v[166:167], v[132:133], v[134:135]
	v_mov_b32_e32 v191, v135
	v_mov_b32_e32 v135, v169
	v_pk_fma_f32 v[136:137], v[170:171], v[172:173], v[136:137] neg_lo:[0,0,1] neg_hi:[0,0,1]
	v_mov_b32_e32 v172, v132
	v_mov_b32_e32 v173, v131
	v_mov_b32_e32 v190, v168
	v_pk_mul_f32 v[134:135], v[192:193], v[134:135]
	v_pk_fma_f32 v[166:167], v[130:131], v[168:169], v[166:167]
	v_pk_fma_f32 v[134:135], v[172:173], v[190:191], v[134:135] neg_lo:[0,0,1] neg_hi:[0,0,1]
	v_pk_mul_f32 v[162:163], v[176:177], v[162:163]
	v_pk_mul_f32 v[136:137], v[176:177], v[136:137]
	v_pk_mul_f32 v[166:167], v[176:177], v[166:167]
	v_pk_mul_f32 v[168:169], v[176:177], v[134:135]
	v_cvt_pk_bf16_f32 v134, v136, v137
	v_cvt_pk_bf16_f32 v135, v168, v169
	v_cvt_pk_bf16_f32 v136, v162, v163
	v_cvt_pk_bf16_f32 v137, v166, v167
	global_store_dwordx4 v[164:165], v[134:137], off
	s_nop 1
	v_pk_mul_f32 v[134:135], v[38:39], v[38:39]
	v_pk_mul_f32 v[136:137], v[36:37], v[36:37]
	s_nop 0
	v_pk_mov_b32 v[162:163], v[136:137], v[134:135] op_sel:[1,0]
	v_mov_b32_e32 v137, v135
	v_pk_add_f32 v[134:135], v[162:163], v[136:137]
	v_pk_mul_f32 v[136:137], v[34:35], v[34:35]
	v_pk_mul_f32 v[162:163], v[32:33], v[32:33]
	v_mov_b32_e32 v166, v136
	v_mov_b32_e32 v167, v162
	v_mov_b32_e32 v162, v137
	v_pk_add_f32 v[136:137], v[166:167], v[162:163]
	v_add_f32_e32 v134, v134, v135
	v_mbcnt_lo_u32_b32 v135, -1, 0
	v_mbcnt_hi_u32_b32 v135, -1, v135
	v_add_f32_e32 v134, v134, v137
	v_lshlrev_b32_e32 v135, 2, v135
	v_add_f32_e32 v134, v136, v134
	v_xor_b32_e32 v135, 64, v135
	ds_bpermute_b32 v135, v135, v134
	s_waitcnt lgkmcnt(0)
	v_add_f32_e32 v134, v134, v135
	v_mbcnt_lo_u32_b32 v135, -1, 0
	v_mbcnt_hi_u32_b32 v135, -1, v135
	s_nop 0
	v_lshlrev_b32_e32 v135, 2, v135
	v_xor_b32_e32 v135, 0x80, v135
	ds_bpermute_b32 v135, v135, v134
	s_waitcnt lgkmcnt(0)
	v_add_f32_e32 v134, v134, v135
	v_fmamk_f32 v134, v134, 0x3d000000, v208
	v_rsq_f32_e32 v134, v134
	s_nop 0
	v_pk_mul_f32 v[136:137], v[38:39], v[134:135] op_sel_hi:[1,0]
	v_pk_mul_f32 v[162:163], v[36:37], v[134:135] op_sel_hi:[1,0]
	v_pk_mul_f32 v[166:167], v[34:35], v[134:135] op_sel_hi:[1,0]
	v_pk_mul_f32 v[134:135], v[32:33], v[134:135] op_sel_hi:[1,0]
	v_mov_b32_e32 v168, v162
	v_mov_b32_e32 v169, v135
	v_mov_b32_e32 v135, v163
	v_pk_mul_f32 v[134:135], v[158:159], v[134:135]
	v_pk_mul_f32 v[168:169], v[174:175], v[168:169]
	v_pk_mul_f32 v[128:129], v[128:129], v[134:135]
	s_nop 0
	v_pk_fma_f32 v[128:129], v[178:179], v[168:169], v[128:129]
	v_mov_b32_e32 v178, 0
	v_pk_mul_f32 v[162:163], v[176:177], v[128:129]
	v_mov_b32_e32 v129, v135
	v_mov_b32_e32 v135, v169
	v_mov_b32_e32 v128, v168
	v_pk_mul_f32 v[134:135], v[180:181], v[134:135]
	v_mov_b32_e32 v180, 0
	v_pk_fma_f32 v[128:129], v[170:171], v[128:129], v[134:135] neg_lo:[0,0,1] neg_hi:[0,0,1]
	v_mov_b32_e32 v135, v167
	v_mov_b32_e32 v167, v137
	v_mov_b32_e32 v134, v136
	v_pk_mul_f32 v[136:137], v[154:155], v[166:167]
	v_pk_mul_f32 v[134:135], v[156:157], v[134:135]
	v_pk_mul_f32 v[132:133], v[132:133], v[136:137]
	v_pk_mul_f32 v[128:129], v[176:177], v[128:129]
	v_pk_fma_f32 v[130:131], v[130:131], v[134:135], v[132:133]
	v_cvt_pk_bf16_f32 v128, v128, v129
	v_pk_mul_f32 v[132:133], v[176:177], v[130:131]
	v_mov_b32_e32 v131, v137
	v_mov_b32_e32 v137, v135
	v_mov_b32_e32 v130, v134
	v_pk_mul_f32 v[134:135], v[192:193], v[136:137]
	v_mov_b32_e32 v181, 1.0
	v_pk_fma_f32 v[130:131], v[172:173], v[130:131], v[134:135] neg_lo:[0,0,1] neg_hi:[0,0,1]
	v_mov_b32_e32 v134, 1.0
	v_pk_mul_f32 v[130:131], v[176:177], v[130:131]
	v_mov_b32_e32 v135, 0
	v_cvt_pk_bf16_f32 v129, v130, v131
	v_cvt_pk_bf16_f32 v130, v162, v163
	v_cvt_pk_bf16_f32 v131, v132, v133
	global_store_dwordx4 v[164:165], v[128:131], off offset:64
	v_mov_b32_e32 v136, 0
	v_mov_b32_e32 v137, 1.0
	v_add_u32_e32 v129, 0xa0, v184
	v_mov_b32_e32 v128, 1.0
	v_mov_b32_e32 v130, 1.0
	v_mov_b32_e32 v131, 0
	s_cbranch_vccnz .LBB0_264
	v_bfe_u32 v130, v129, 6, 7
	v_cndmask_b32_e64 v130, v187, v130, s[42:43]
	v_cmp_ne_u32_e64 s[98:99], 0, v153
	v_cvt_f32_u32_e32 v132, v130
	v_mov_b32_e32 v133, 0x3c23d70a
	v_cndmask_b32_e64 v133, 1.0, v133, s[98:99]
	v_mul_f32_e32 v132, v132, v133
	v_mul_f32_e32 v135, 0x3e22f983, v132
	v_cos_f32_e32 v134, v135
	v_sin_f32_e32 v135, v135
	v_mul_f32_e32 v137, 0x3d4e2601, v132
	v_cos_f32_e32 v136, v137
	v_sin_f32_e32 v137, v137
	v_mul_f32_e32 v131, 0x3c826136, v132
	v_cos_f32_e32 v130, v131
	v_sin_f32_e32 v131, v131
	v_mul_f32_e32 v133, 0x3ba4eb34, v132
	v_cos_f32_e32 v132, v133
	v_sin_f32_e32 v133, v133
	s_nop 0
	v_mov_b32_e32 v180, v135
	v_mov_b32_e32 v181, v136
	v_mov_b32_e32 v135, v137
	v_mov_b32_e32 v136, v131
	v_mov_b32_e32 v137, v132
	v_mov_b32_e32 v131, v133
.LBB0_264:
	v_pk_mul_f32 v[132:133], v[30:31], v[30:31]
	v_pk_mul_f32 v[162:163], v[28:29], v[28:29]
	v_readlane_b32 s22, v252, 52
	v_pk_mov_b32 v[164:165], v[162:163], v[132:133] op_sel:[1,0]
	v_mov_b32_e32 v163, v133
	v_pk_add_f32 v[132:133], v[164:165], v[162:163]
	v_pk_mul_f32 v[162:163], v[26:27], v[26:27]
	v_pk_mul_f32 v[164:165], v[24:25], v[24:25]
	v_mov_b32_e32 v166, v162
	v_mov_b32_e32 v167, v164
	v_mov_b32_e32 v164, v163
	v_pk_add_f32 v[162:163], v[166:167], v[164:165]
	v_add_f32_e32 v132, v132, v133
	v_mbcnt_lo_u32_b32 v133, -1, 0
	v_mbcnt_hi_u32_b32 v133, -1, v133
	v_add_f32_e32 v132, v132, v163
	v_lshlrev_b32_e32 v133, 2, v133
	v_add_f32_e32 v132, v162, v132
	v_xor_b32_e32 v133, 64, v133
	ds_bpermute_b32 v133, v133, v132
	v_readlane_b32 s23, v252, 53
	v_mov_b32_e32 v194, v180
	v_mov_b32_e32 v195, v135
	v_mov_b32_e32 v172, v134
	s_waitcnt lgkmcnt(0)
	v_add_f32_e32 v162, v132, v133
	v_mbcnt_lo_u32_b32 v132, -1, 0
	v_mbcnt_hi_u32_b32 v132, -1, v132
	v_mov_b32_e32 v173, v181
	v_lshlrev_b32_e32 v132, 2, v132
	v_xor_b32_e32 v132, 0x80, v132
	ds_bpermute_b32 v163, v132, v162
	v_mov_b64_e32 v[132:133], s[22:23]
	v_mad_i64_i32 v[132:133], s[22:23], v129, s71, v[132:133]
	v_lshl_add_u64 v[164:165], v[150:151], 1, v[132:133]
	s_waitcnt lgkmcnt(0)
	v_add_f32_e32 v162, v162, v163
	v_fmamk_f32 v162, v162, 0x3d000000, v208
	v_rsq_f32_e32 v162, v162
	v_mov_b32_e32 v196, v136
	v_mov_b32_e32 v197, v131
	s_and_b64 vcc, exec, s[0:1]
	v_pk_mul_f32 v[132:133], v[30:31], v[162:163] op_sel_hi:[1,0]
	v_pk_mul_f32 v[166:167], v[28:29], v[162:163] op_sel_hi:[1,0]
	v_pk_mul_f32 v[168:169], v[26:27], v[162:163] op_sel_hi:[1,0]
	v_pk_mul_f32 v[162:163], v[24:25], v[162:163] op_sel_hi:[1,0]
	v_mov_b32_e32 v170, v166
	v_mov_b32_e32 v171, v163
	v_mov_b32_e32 v163, v167
	v_pk_mul_f32 v[162:163], v[158:159], v[162:163]
	v_pk_mul_f32 v[170:171], v[174:175], v[170:171]
	v_pk_mul_f32 v[166:167], v[134:135], v[162:163]
	v_mov_b32_e32 v186, v170
	v_pk_fma_f32 v[166:167], v[180:181], v[170:171], v[166:167]
	v_mov_b32_e32 v187, v163
	v_mov_b32_e32 v163, v171
	v_mov_b32_e32 v170, v132
	v_mov_b32_e32 v171, v169
	v_mov_b32_e32 v169, v133
	v_pk_mul_f32 v[170:171], v[156:157], v[170:171]
	v_pk_mul_f32 v[132:133], v[154:155], v[168:169]
	v_pk_mul_f32 v[162:163], v[194:195], v[162:163]
	v_pk_mul_f32 v[168:169], v[130:131], v[132:133]
	v_mov_b32_e32 v191, v133
	v_mov_b32_e32 v133, v171
	v_pk_fma_f32 v[162:163], v[172:173], v[186:187], v[162:163] neg_lo:[0,0,1] neg_hi:[0,0,1]
	v_mov_b32_e32 v186, v130
	v_mov_b32_e32 v187, v137
	v_mov_b32_e32 v190, v170
	v_pk_mul_f32 v[132:133], v[196:197], v[132:133]
	v_pk_mul_f32 v[162:163], v[176:177], v[162:163]
	v_pk_fma_f32 v[132:133], v[186:187], v[190:191], v[132:133] neg_lo:[0,0,1] neg_hi:[0,0,1]
	v_pk_mul_f32 v[166:167], v[176:177], v[166:167]
	v_pk_mul_f32 v[132:133], v[176:177], v[132:133]
	v_cvt_pk_bf16_f32 v190, v162, v163
	v_cvt_pk_bf16_f32 v191, v132, v133
	v_pk_mul_f32 v[132:133], v[22:23], v[22:23]
	v_pk_mul_f32 v[162:163], v[20:21], v[20:21]
	v_pk_fma_f32 v[168:169], v[136:137], v[170:171], v[168:169]
	v_cvt_pk_bf16_f32 v192, v166, v167
	v_pk_mov_b32 v[166:167], v[162:163], v[132:133] op_sel:[1,0]
	v_mov_b32_e32 v163, v133
	v_pk_mul_f32 v[168:169], v[176:177], v[168:169]
	v_pk_add_f32 v[132:133], v[166:167], v[162:163]
	v_pk_mul_f32 v[162:163], v[18:19], v[18:19]
	v_pk_mul_f32 v[166:167], v[16:17], v[16:17]
	v_cvt_pk_bf16_f32 v193, v168, v169
	v_mov_b32_e32 v168, v162
	v_mov_b32_e32 v169, v166
	v_mov_b32_e32 v166, v163
	global_store_dwordx4 v[164:165], v[190:193], off
	v_pk_add_f32 v[162:163], v[168:169], v[166:167]
	v_add_f32_e32 v129, v132, v133
	v_mbcnt_lo_u32_b32 v132, -1, 0
	v_mbcnt_hi_u32_b32 v132, -1, v132
	v_add_f32_e32 v129, v129, v163
	v_lshlrev_b32_e32 v132, 2, v132
	v_add_f32_e32 v129, v162, v129
	v_xor_b32_e32 v132, 64, v132
	ds_bpermute_b32 v132, v132, v129
	v_mov_b32_e32 v179, 1.0
	s_waitcnt lgkmcnt(0)
	v_add_f32_e32 v129, v129, v132
	v_mbcnt_lo_u32_b32 v132, -1, 0
	v_mbcnt_hi_u32_b32 v132, -1, v132
	s_nop 0
	v_lshlrev_b32_e32 v132, 2, v132
	v_xor_b32_e32 v132, 0x80, v132
	ds_bpermute_b32 v132, v132, v129
	s_waitcnt lgkmcnt(0)
	v_add_f32_e32 v129, v129, v132
	v_fmamk_f32 v129, v129, 0x3d000000, v208
	v_rsq_f32_e32 v132, v129
	v_mov_b32_e32 v129, 0
	v_pk_mul_f32 v[162:163], v[22:23], v[132:133] op_sel_hi:[1,0]
	v_pk_mul_f32 v[166:167], v[20:21], v[132:133] op_sel_hi:[1,0]
	v_pk_mul_f32 v[168:169], v[18:19], v[132:133] op_sel_hi:[1,0]
	v_pk_mul_f32 v[132:133], v[16:17], v[132:133] op_sel_hi:[1,0]
	v_mov_b32_e32 v170, v166
	v_mov_b32_e32 v171, v133
	v_mov_b32_e32 v133, v167
	v_pk_mul_f32 v[170:171], v[174:175], v[170:171]
	v_pk_mul_f32 v[132:133], v[158:159], v[132:133]
	v_mov_b32_e32 v166, v170
	v_pk_mul_f32 v[134:135], v[134:135], v[132:133]
	v_mov_b32_e32 v167, v133
	v_mov_b32_e32 v133, v171
	v_pk_mul_f32 v[132:133], v[194:195], v[132:133]
	v_pk_fma_f32 v[134:135], v[180:181], v[170:171], v[134:135]
	v_pk_fma_f32 v[132:133], v[172:173], v[166:167], v[132:133] neg_lo:[0,0,1] neg_hi:[0,0,1]
	v_mov_b32_e32 v167, v169
	v_mov_b32_e32 v169, v163
	v_mov_b32_e32 v166, v162
	v_pk_mul_f32 v[162:163], v[154:155], v[168:169]
	v_pk_mul_f32 v[166:167], v[156:157], v[166:167]
	v_pk_mul_f32 v[130:131], v[130:131], v[162:163]
	v_pk_mul_f32 v[134:135], v[176:177], v[134:135]
	v_pk_fma_f32 v[130:131], v[136:137], v[166:167], v[130:131]
	v_pk_mul_f32 v[132:133], v[176:177], v[132:133]
	v_pk_mul_f32 v[136:137], v[176:177], v[130:131]
	v_mov_b32_e32 v131, v163
	v_mov_b32_e32 v163, v167
	v_mov_b32_e32 v130, v166
	v_pk_mul_f32 v[162:163], v[196:197], v[162:163]
	s_nop 0
	v_pk_fma_f32 v[130:131], v[186:187], v[130:131], v[162:163] neg_lo:[0,0,1] neg_hi:[0,0,1]
	s_nop 0
	v_pk_mul_f32 v[162:163], v[176:177], v[130:131]
	v_cvt_pk_bf16_f32 v130, v132, v133
	v_cvt_pk_bf16_f32 v131, v162, v163
	v_cvt_pk_bf16_f32 v132, v134, v135
	v_cvt_pk_bf16_f32 v133, v136, v137
	global_store_dwordx4 v[164:165], v[130:133], off offset:64
	v_add_u32_e32 v136, 0xb0, v184
	s_nop 0
	v_mov_b32_e32 v132, 1.0
	v_mov_b32_e32 v130, 0
	v_mov_b32_e32 v131, 1.0
	v_mov_b32_e32 v133, 0
	s_cbranch_vccnz .LBB0_266
	v_bfe_u32 v128, v136, 6, 7
	v_cndmask_b32_e64 v128, v188, v128, s[42:43]
	v_cmp_ne_u32_e64 s[98:99], 0, v153
	v_cvt_f32_u32_e32 v134, v128
	v_mov_b32_e32 v135, 0x3c23d70a
	v_cndmask_b32_e64 v135, 1.0, v135, s[98:99]
	v_mul_f32_e32 v134, v134, v135
	v_mul_f32_e32 v129, 0x3e22f983, v134
	v_cos_f32_e32 v128, v129
	v_sin_f32_e32 v129, v129
	v_mul_f32_e32 v131, 0x3d4e2601, v134
	v_cos_f32_e32 v130, v131
	v_sin_f32_e32 v131, v131
	v_mul_f32_e32 v133, 0x3c826136, v134
	v_cos_f32_e32 v132, v133
	v_sin_f32_e32 v133, v133
	v_mul_f32_e32 v135, 0x3ba4eb34, v134
	v_cos_f32_e32 v134, v135
	v_sin_f32_e32 v135, v135
	s_nop 0
	v_mov_b32_e32 v178, v129
	v_mov_b32_e32 v179, v130
	v_mov_b32_e32 v129, v131
	v_mov_b32_e32 v130, v133
	v_mov_b32_e32 v131, v134
	v_mov_b32_e32 v133, v135

	.amdhsa_kernel _Z7hyb_fwd4Args
		.amdhsa_group_segment_fixed_size 0
		.amdhsa_private_segment_fixed_size 0
		.amdhsa_kernarg_size 448
		.amdhsa_user_sgpr_count 2
		.amdhsa_user_sgpr_dispatch_ptr 0
		.amdhsa_user_sgpr_queue_ptr 0
		.amdhsa_user_sgpr_kernarg_segment_ptr 1
		.amdhsa_user_sgpr_dispatch_id 0
		.amdhsa_user_sgpr_kernarg_preload_length 0
		.amdhsa_user_sgpr_kernarg_preload_offset 0
		.amdhsa_user_sgpr_private_segment_size 0
		.amdhsa_uses_dynamic_stack 0
		.amdhsa_enable_private_segment 0
		.amdhsa_system_sgpr_workgroup_id_x 1
		.amdhsa_system_sgpr_workgroup_id_y 0
		.amdhsa_system_sgpr_workgroup_id_z 0
		.amdhsa_system_sgpr_workgroup_info 0
		.amdhsa_system_vgpr_workitem_id 0
		.amdhsa_next_free_vgpr 256
		.amdhsa_next_free_sgpr 102
		.amdhsa_accum_offset 256
		.amdhsa_reserve_vcc 1
		.amdhsa_float_round_mode_32 0
		.amdhsa_float_round_mode_16_64 0
		.amdhsa_float_denorm_mode_32 3
		.amdhsa_float_denorm_mode_16_64 3
		.amdhsa_dx10_clamp 1
		.amdhsa_ieee_mode 1
		.amdhsa_fp16_overflow 0
		.amdhsa_tg_split 0
		.amdhsa_exception_fp_ieee_invalid_op 0
		.amdhsa_exception_fp_denorm_src 0
		.amdhsa_exception_fp_ieee_div_zero 0
		.amdhsa_exception_fp_ieee_overflow 0
		.amdhsa_exception_fp_ieee_underflow 0
		.amdhsa_exception_fp_ieee_inexact 0
		.amdhsa_exception_int_div_zero 0
	.end_amdhsa_kernel

amdhsa.kernels:
  - .agpr_count:     0
    .args:
      - .offset:         0
        .size:           192
        .value_kind:     by_value
      - .offset:         192
        .size:           4
        .value_kind:     hidden_block_count_x
      - .offset:         196
        .size:           4
        .value_kind:     hidden_block_count_y
      - .offset:         200
        .size:           4
        .value_kind:     hidden_block_count_z
      - .offset:         204
        .size:           2
        .value_kind:     hidden_group_size_x
      - .offset:         206
        .size:           2
        .value_kind:     hidden_group_size_y
      - .offset:         208
        .size:           2
        .value_kind:     hidden_group_size_z
      - .offset:         210
        .size:           2
        .value_kind:     hidden_remainder_x
      - .offset:         212
        .size:           2
        .value_kind:     hidden_remainder_y
      - .offset:         214
        .size:           2
        .value_kind:     hidden_remainder_z
      - .offset:         232
        .size:           8
        .value_kind:     hidden_global_offset_x
      - .offset:         240
        .size:           8
        .value_kind:     hidden_global_offset_y
      - .offset:         248
        .size:           8
        .value_kind:     hidden_global_offset_z
      - .offset:         256
        .size:           2
        .value_kind:     hidden_grid_dims
      - .offset:         312
        .size:           4
        .value_kind:     hidden_dynamic_lds_size
    .group_segment_fixed_size: 0
    .kernarg_segment_align: 8
    .kernarg_segment_size: 448
    .language:       OpenCL C
    .language_version:
      - 2
      - 0
    .max_flat_workgroup_size: 512
    .name:           _Z7hyb_fwd4Args
    .private_segment_fixed_size: 0
    .sgpr_count:     108
    .sgpr_spill_count: 369
    .symbol:         _Z7hyb_fwd4Args.kd
    .uniform_work_group_size: 1
    .uses_dynamic_stack: false
    .vgpr_count:     256
    .vgpr_spill_count: 0
    .wavefront_size: 64
